# GEMM4a K-loop: VALU address adds folded into SGPR-base LDS-DMA requests (completes the set of six K-loops)
# speedup vs baseline: 1.0129x; 1.0026x over previous
.LBB0_743:
	s_ashr_i32 s35, s34, 31
	s_lshl_b64 s[36:37], s[34:35], 17
	s_add_u32 s36, s13, s36
	s_addc_u32 s37, s22, s37
	s_and_b64 s[38:39], s[4:5], exec
	s_cselect_b32 s35, s37, s43
	s_cselect_b32 s82, s36, s42
	s_ashr_i32 s31, s30, 31
	s_lshl_b64 s[38:39], s[30:31], 17
	s_add_u32 s38, s23, s38
	s_addc_u32 s39, s58, s39
	s_and_b64 s[44:45], s[4:5], exec
	s_cselect_b32 s31, s39, s41
	s_cselect_b32 s83, s38, s40
	s_mov_b64 s[48:49], 0
	s_mov_b64 s[44:45], -1
	s_mov_b64 s[46:47], 0
	s_add_u32 s54, s42, s48
	s_addc_u32 s55, s43, s49
	s_add_u32 s52, s54, 0x100
	s_addc_u32 s53, s55, 0
	s_and_b64 s[50:51], s[46:47], exec
	s_cselect_b32 s51, s35, s53
	s_cselect_b32 s50, s82, s52
	s_add_u32 s48, s40, s48
	s_addc_u32 s49, s41, s49
	s_add_u32 s48, s48, 0x100
	s_addc_u32 s49, s49, 0
	s_and_b64 s[46:47], s[46:47], exec
	s_cselect_b32 s53, s31, s49
	s_cselect_b32 s52, s83, s48
	s_cselect_b32 s98, 1, 0
	s_add_u32 s56, s54, 0x10080
	ds_read_b128 v[150:153], v144
	ds_read_b128 v[154:157], v144 offset:1024
	ds_read_b128 v[158:161], v144 offset:2048
	ds_read_b128 v[162:165], v144 offset:3072
	ds_read_b128 v[166:169], v145
	ds_read_b128 v[170:173], v145 offset:1024
	ds_read_b128 v[174:177], v145 offset:2048
	ds_read_b128 v[178:181], v145 offset:3072
	s_addc_u32 s57, s55, 0
	s_add_i32 s93, s74, s60
	s_add_i32 m0, s61, 0xc000
	s_add_i32 s94, s61, 0xe000
	s_add_i32 s90, s93, 0x2000
	s_add_u32 s54, s52, 0x10000
	s_addc_u32 s55, s53, 0
	s_add_i32 s92, s75, s60
	s_add_i32 s91, s92, 0x2000
	s_add_i32 s89, 0, 0x18000
	s_add_i32 s88, 0, 0x1c000
	s_add_u32 s48, s50, 0x10000
	s_addc_u32 s49, s51, 0
	s_add_i32 s87, s89, s60
	s_add_i32 s85, s87, 0x2000
	s_add_u32 s46, s52, 0x10080
	s_addc_u32 s47, s53, 0
	s_add_i32 s86, s88, s60
	s_add_i32 s84, s86, 0x2000
	ds_read_b128 v[182:185], v146
	ds_read_b128 v[186:189], v146 offset:1024
	ds_read_b128 v[190:193], v146 offset:2048
	ds_read_b128 v[194:197], v146 offset:3072
	ds_read_b128 v[198:201], v146 offset:4096
	ds_read_b128 v[202:205], v146 offset:5120
	ds_read_b128 v[206:209], v146 offset:6144
	ds_read_b128 v[210:213], v146 offset:7168
	global_load_lds_dwordx4 v130, s[56:57]
	s_mov_b32 m0, s94
	s_nop 0
	global_load_lds_dwordx4 v128, s[56:57]
	s_waitcnt vmcnt(8)
	s_waitcnt lgkmcnt(0)
	s_setprio 1
	s_cmp_lg_u32 s98, 0
	s_cbranch_scc0 .Lkv_nopf_pk
	v_lshl_add_u32 v138, s18, 8, v141
	v_ashrrev_i32_e32 v139, 31, v138
	v_lshl_add_u64 v[138:139], v[138:139], 4, s[14:15]
	global_load_dwordx4 v[222:225], v[138:139], off
	global_load_dwordx4 v[226:229], v[138:139], off offset:256
	global_load_dwordx4 v[230:233], v[138:139], off offset:512
	global_load_dwordx4 v[234:237], v[138:139], off offset:768
	global_load_dwordx4 v[238:241], v[138:139], off offset:2048
	global_load_dwordx4 v[242:245], v[138:139], off offset:2304
	global_load_dwordx4 v[248:251], v[138:139], off offset:2560
	global_load_dwordx4 v[252:255], v[138:139], off offset:2816
.Lkv_nopf_pk:
	s_barrier
	v_mfma_f32_16x16x32_bf16 v[124:127], v[150:153], v[182:185], 0
	v_mfma_f32_16x16x32_bf16 v[120:123], v[158:161], v[182:185], 0
	v_mfma_f32_16x16x32_bf16 v[108:111], v[150:153], v[190:193], 0
	v_mfma_f32_16x16x32_bf16 v[104:107], v[158:161], v[190:193], 0
	v_mfma_f32_16x16x32_bf16 v[92:95], v[150:153], v[198:201], 0
	v_mfma_f32_16x16x32_bf16 v[88:91], v[158:161], v[198:201], 0
	v_mfma_f32_16x16x32_bf16 v[76:79], v[150:153], v[206:209], 0
	v_mfma_f32_16x16x32_bf16 v[72:75], v[158:161], v[206:209], 0
	v_mfma_f32_16x16x32_bf16 v[124:127], v[154:157], v[186:189], v[124:127]
	v_mfma_f32_16x16x32_bf16 v[120:123], v[162:165], v[186:189], v[120:123]
	v_mfma_f32_16x16x32_bf16 v[108:111], v[154:157], v[194:197], v[108:111]
	v_mfma_f32_16x16x32_bf16 v[104:107], v[162:165], v[194:197], v[104:107]
	v_mfma_f32_16x16x32_bf16 v[92:95], v[154:157], v[202:205], v[92:95]
	v_mfma_f32_16x16x32_bf16 v[88:91], v[162:165], v[202:205], v[88:91]
	v_mfma_f32_16x16x32_bf16 v[76:79], v[154:157], v[210:213], v[76:79]
	v_mfma_f32_16x16x32_bf16 v[72:75], v[162:165], v[210:213], v[72:75]
	v_mfma_f32_16x16x32_bf16 v[116:119], v[166:169], v[182:185], 0
	v_mfma_f32_16x16x32_bf16 v[112:115], v[174:177], v[182:185], 0
	v_mfma_f32_16x16x32_bf16 v[100:103], v[166:169], v[190:193], 0
	v_mfma_f32_16x16x32_bf16 v[96:99], v[174:177], v[190:193], 0
	v_mfma_f32_16x16x32_bf16 v[84:87], v[166:169], v[198:201], 0
	v_mfma_f32_16x16x32_bf16 v[80:83], v[174:177], v[198:201], 0
	v_mfma_f32_16x16x32_bf16 v[68:71], v[166:169], v[206:209], 0
	v_mfma_f32_16x16x32_bf16 v[64:67], v[174:177], v[206:209], 0
	v_mfma_f32_16x16x32_bf16 v[116:119], v[170:173], v[186:189], v[116:119]
	v_mfma_f32_16x16x32_bf16 v[112:115], v[178:181], v[186:189], v[112:115]
	v_mfma_f32_16x16x32_bf16 v[100:103], v[170:173], v[194:197], v[100:103]
	v_mfma_f32_16x16x32_bf16 v[96:99], v[178:181], v[194:197], v[96:99]
	v_mfma_f32_16x16x32_bf16 v[84:87], v[170:173], v[202:205], v[84:87]
	v_mfma_f32_16x16x32_bf16 v[80:83], v[178:181], v[202:205], v[80:83]
	v_mfma_f32_16x16x32_bf16 v[68:71], v[170:173], v[210:213], v[68:71]
	v_mfma_f32_16x16x32_bf16 v[64:67], v[178:181], v[210:213], v[64:67]
	s_barrier
	s_setprio 0
	s_mov_b32 m0, s93
	s_add_u32 s98, s52, 0x80
	s_addc_u32 s99, s53, 0
	ds_read_b128 v[182:185], v146 offset:16384
	ds_read_b128 v[186:189], v146 offset:17408
	ds_read_b128 v[190:193], v146 offset:18432
	ds_read_b128 v[194:197], v146 offset:19456
	ds_read_b128 v[198:201], v146 offset:20480
	ds_read_b128 v[202:205], v146 offset:21504
	ds_read_b128 v[206:209], v146 offset:22528
	ds_read_b128 v[210:213], v146 offset:23552
	global_load_lds_dwordx4 v130, s[52:53]
	s_mov_b32 m0, s90
	s_nop 0
	global_load_lds_dwordx4 v128, s[52:53]
	s_mov_b32 m0, s92
	s_add_u32 s100, s50, 0x80
	s_addc_u32 s101, s51, 0
	global_load_lds_dwordx4 v130, s[54:55]
	s_mov_b32 m0, s91
	s_nop 0
	global_load_lds_dwordx4 v128, s[54:55]
	s_mov_b32 m0, s61
	s_nop 0
	global_load_lds_dwordx4 v130, s[50:51]
	s_mov_b32 m0, s62
	s_nop 0
	global_load_lds_dwordx4 v128, s[50:51]
	s_waitcnt vmcnt(8)
	s_waitcnt lgkmcnt(0)
	s_setprio 1
	s_barrier
	v_mfma_f32_16x16x32_bf16 v[60:63], v[150:153], v[182:185], 0
	v_mfma_f32_16x16x32_bf16 v[56:59], v[158:161], v[182:185], 0
	v_mfma_f32_16x16x32_bf16 v[44:47], v[150:153], v[190:193], 0
	v_mfma_f32_16x16x32_bf16 v[40:43], v[158:161], v[190:193], 0
	v_mfma_f32_16x16x32_bf16 v[28:31], v[150:153], v[198:201], 0
	v_mfma_f32_16x16x32_bf16 v[24:27], v[158:161], v[198:201], 0
	v_mfma_f32_16x16x32_bf16 v[12:15], v[150:153], v[206:209], 0
	v_mfma_f32_16x16x32_bf16 v[8:11], v[158:161], v[206:209], 0
	v_mfma_f32_16x16x32_bf16 v[60:63], v[154:157], v[186:189], v[60:63]
	v_mfma_f32_16x16x32_bf16 v[56:59], v[162:165], v[186:189], v[56:59]
	v_mfma_f32_16x16x32_bf16 v[44:47], v[154:157], v[194:197], v[44:47]
	v_mfma_f32_16x16x32_bf16 v[40:43], v[162:165], v[194:197], v[40:43]
	v_mfma_f32_16x16x32_bf16 v[28:31], v[154:157], v[202:205], v[28:31]
	v_mfma_f32_16x16x32_bf16 v[24:27], v[162:165], v[202:205], v[24:27]
	v_mfma_f32_16x16x32_bf16 v[12:15], v[154:157], v[210:213], v[12:15]
	v_mfma_f32_16x16x32_bf16 v[8:11], v[162:165], v[210:213], v[8:11]
	v_mfma_f32_16x16x32_bf16 v[52:55], v[166:169], v[182:185], 0
	v_mfma_f32_16x16x32_bf16 v[48:51], v[174:177], v[182:185], 0
	v_mfma_f32_16x16x32_bf16 v[36:39], v[166:169], v[190:193], 0
	v_mfma_f32_16x16x32_bf16 v[32:35], v[174:177], v[190:193], 0
	v_mfma_f32_16x16x32_bf16 v[20:23], v[166:169], v[198:201], 0
	v_mfma_f32_16x16x32_bf16 v[16:19], v[174:177], v[198:201], 0
	v_mfma_f32_16x16x32_bf16 v[4:7], v[166:169], v[206:209], 0
	v_mfma_f32_16x16x32_bf16 v[0:3], v[174:177], v[206:209], 0
	v_mfma_f32_16x16x32_bf16 v[52:55], v[170:173], v[186:189], v[52:55]
	v_mfma_f32_16x16x32_bf16 v[48:51], v[178:181], v[186:189], v[48:51]
	v_mfma_f32_16x16x32_bf16 v[36:39], v[170:173], v[194:197], v[36:39]
	v_mfma_f32_16x16x32_bf16 v[32:35], v[178:181], v[194:197], v[32:35]
	v_mfma_f32_16x16x32_bf16 v[20:23], v[170:173], v[202:205], v[20:23]
	v_mfma_f32_16x16x32_bf16 v[16:19], v[178:181], v[202:205], v[16:19]
	v_mfma_f32_16x16x32_bf16 v[4:7], v[170:173], v[210:213], v[4:7]
	v_mfma_f32_16x16x32_bf16 v[0:3], v[178:181], v[210:213], v[0:3]
	s_barrier
	s_setprio 0
	v_add_u32_e32 v132, s89, v143
	ds_read_b128 v[150:153], v132
	ds_read_b128 v[154:157], v132 offset:1024
	ds_read_b128 v[158:161], v132 offset:2048
	ds_read_b128 v[162:165], v132 offset:3072
	v_add_u32_e32 v132, s88, v143
	ds_read_b128 v[166:169], v132
	ds_read_b128 v[170:173], v132 offset:1024
	ds_read_b128 v[174:177], v132 offset:2048
	ds_read_b128 v[178:181], v132 offset:3072
	s_mov_b32 m0, s63
	ds_read_b128 v[182:185], v146 offset:32768
	ds_read_b128 v[186:189], v146 offset:33792
	ds_read_b128 v[190:193], v146 offset:34816
	ds_read_b128 v[194:197], v146 offset:35840
	ds_read_b128 v[198:201], v146 offset:36864
	ds_read_b128 v[202:205], v146 offset:37888
	ds_read_b128 v[206:209], v146 offset:38912
	ds_read_b128 v[210:213], v146 offset:39936
	global_load_lds_dwordx4 v130, s[48:49]
	s_mov_b32 m0, s64
	s_nop 0
	global_load_lds_dwordx4 v128, s[48:49]
	s_waitcnt vmcnt(8)
	s_waitcnt lgkmcnt(0)
	s_setprio 1
	s_barrier
	v_mfma_f32_16x16x32_bf16 v[124:127], v[150:153], v[182:185], v[124:127]
	v_mfma_f32_16x16x32_bf16 v[120:123], v[158:161], v[182:185], v[120:123]
	v_mfma_f32_16x16x32_bf16 v[108:111], v[150:153], v[190:193], v[108:111]
	v_mfma_f32_16x16x32_bf16 v[104:107], v[158:161], v[190:193], v[104:107]
	v_mfma_f32_16x16x32_bf16 v[92:95], v[150:153], v[198:201], v[92:95]
	v_mfma_f32_16x16x32_bf16 v[88:91], v[158:161], v[198:201], v[88:91]
	v_mfma_f32_16x16x32_bf16 v[76:79], v[150:153], v[206:209], v[76:79]
	v_mfma_f32_16x16x32_bf16 v[72:75], v[158:161], v[206:209], v[72:75]
	v_mfma_f32_16x16x32_bf16 v[124:127], v[154:157], v[186:189], v[124:127]
	v_mfma_f32_16x16x32_bf16 v[120:123], v[162:165], v[186:189], v[120:123]
	v_mfma_f32_16x16x32_bf16 v[108:111], v[154:157], v[194:197], v[108:111]
	v_mfma_f32_16x16x32_bf16 v[104:107], v[162:165], v[194:197], v[104:107]
	v_mfma_f32_16x16x32_bf16 v[92:95], v[154:157], v[202:205], v[92:95]
	v_mfma_f32_16x16x32_bf16 v[88:91], v[162:165], v[202:205], v[88:91]
	v_mfma_f32_16x16x32_bf16 v[76:79], v[154:157], v[210:213], v[76:79]
	v_mfma_f32_16x16x32_bf16 v[72:75], v[162:165], v[210:213], v[72:75]
	v_mfma_f32_16x16x32_bf16 v[116:119], v[166:169], v[182:185], v[116:119]
	v_mfma_f32_16x16x32_bf16 v[112:115], v[174:177], v[182:185], v[112:115]
	v_mfma_f32_16x16x32_bf16 v[100:103], v[166:169], v[190:193], v[100:103]
	v_mfma_f32_16x16x32_bf16 v[96:99], v[174:177], v[190:193], v[96:99]
	v_mfma_f32_16x16x32_bf16 v[84:87], v[166:169], v[198:201], v[84:87]
	v_mfma_f32_16x16x32_bf16 v[80:83], v[174:177], v[198:201], v[80:83]
	v_mfma_f32_16x16x32_bf16 v[68:71], v[166:169], v[206:209], v[68:71]
	v_mfma_f32_16x16x32_bf16 v[64:67], v[174:177], v[206:209], v[64:67]
	v_mfma_f32_16x16x32_bf16 v[116:119], v[170:173], v[186:189], v[116:119]
	v_mfma_f32_16x16x32_bf16 v[112:115], v[178:181], v[186:189], v[112:115]
	v_mfma_f32_16x16x32_bf16 v[100:103], v[170:173], v[194:197], v[100:103]
	v_mfma_f32_16x16x32_bf16 v[96:99], v[178:181], v[194:197], v[96:99]
	v_mfma_f32_16x16x32_bf16 v[84:87], v[170:173], v[202:205], v[84:87]
	v_mfma_f32_16x16x32_bf16 v[80:83], v[178:181], v[202:205], v[80:83]
	v_mfma_f32_16x16x32_bf16 v[68:71], v[170:173], v[210:213], v[68:71]
	v_mfma_f32_16x16x32_bf16 v[64:67], v[178:181], v[210:213], v[64:67]
	s_barrier
	s_setprio 0
	s_mov_b32 m0, s87
	ds_read_b128 v[182:185], v146 offset:49152
	ds_read_b128 v[186:189], v146 offset:50176
	ds_read_b128 v[190:193], v146 offset:51200
	ds_read_b128 v[194:197], v146 offset:52224
	ds_read_b128 v[198:201], v146 offset:53248
	ds_read_b128 v[202:205], v146 offset:54272
	ds_read_b128 v[206:209], v146 offset:55296
	ds_read_b128 v[210:213], v146 offset:56320
	global_load_lds_dwordx4 v130, s[98:99]
	s_mov_b32 m0, s85
	s_nop 0
	global_load_lds_dwordx4 v128, s[98:99]
	s_mov_b32 m0, s86
	s_nop 0
	global_load_lds_dwordx4 v130, s[46:47]
	s_mov_b32 m0, s84
	s_nop 0
	global_load_lds_dwordx4 v128, s[46:47]
	s_mov_b32 m0, s70
	s_nop 0
	global_load_lds_dwordx4 v130, s[100:101]
	s_mov_b32 m0, s71
	s_nop 0
	global_load_lds_dwordx4 v128, s[100:101]
	s_waitcnt vmcnt(8)
	s_waitcnt lgkmcnt(0)
	s_setprio 1
	s_barrier
	v_mfma_f32_16x16x32_bf16 v[60:63], v[150:153], v[182:185], v[60:63]
	v_mfma_f32_16x16x32_bf16 v[56:59], v[158:161], v[182:185], v[56:59]
	v_mfma_f32_16x16x32_bf16 v[44:47], v[150:153], v[190:193], v[44:47]
	v_mfma_f32_16x16x32_bf16 v[40:43], v[158:161], v[190:193], v[40:43]
	v_mfma_f32_16x16x32_bf16 v[28:31], v[150:153], v[198:201], v[28:31]
	v_mfma_f32_16x16x32_bf16 v[24:27], v[158:161], v[198:201], v[24:27]
	v_mfma_f32_16x16x32_bf16 v[12:15], v[150:153], v[206:209], v[12:15]
	v_mfma_f32_16x16x32_bf16 v[8:11], v[158:161], v[206:209], v[8:11]
	v_mfma_f32_16x16x32_bf16 v[60:63], v[154:157], v[186:189], v[60:63]
	v_mfma_f32_16x16x32_bf16 v[56:59], v[162:165], v[186:189], v[56:59]
	v_mfma_f32_16x16x32_bf16 v[44:47], v[154:157], v[194:197], v[44:47]
	v_mfma_f32_16x16x32_bf16 v[40:43], v[162:165], v[194:197], v[40:43]
	v_mfma_f32_16x16x32_bf16 v[28:31], v[154:157], v[202:205], v[28:31]
	v_mfma_f32_16x16x32_bf16 v[24:27], v[162:165], v[202:205], v[24:27]
	v_mfma_f32_16x16x32_bf16 v[12:15], v[154:157], v[210:213], v[12:15]
	v_mfma_f32_16x16x32_bf16 v[8:11], v[162:165], v[210:213], v[8:11]
	v_mfma_f32_16x16x32_bf16 v[52:55], v[166:169], v[182:185], v[52:55]
	v_mfma_f32_16x16x32_bf16 v[48:51], v[174:177], v[182:185], v[48:51]
	v_mfma_f32_16x16x32_bf16 v[36:39], v[166:169], v[190:193], v[36:39]
	v_mfma_f32_16x16x32_bf16 v[32:35], v[174:177], v[190:193], v[32:35]
	v_mfma_f32_16x16x32_bf16 v[20:23], v[166:169], v[198:201], v[20:23]
	v_mfma_f32_16x16x32_bf16 v[16:19], v[174:177], v[198:201], v[16:19]
	v_mfma_f32_16x16x32_bf16 v[4:7], v[166:169], v[206:209], v[4:7]
	v_mfma_f32_16x16x32_bf16 v[0:3], v[174:177], v[206:209], v[0:3]
	v_mfma_f32_16x16x32_bf16 v[52:55], v[170:173], v[186:189], v[52:55]
	v_mfma_f32_16x16x32_bf16 v[48:51], v[178:181], v[186:189], v[48:51]
	v_mfma_f32_16x16x32_bf16 v[36:39], v[170:173], v[194:197], v[36:39]
	v_mfma_f32_16x16x32_bf16 v[32:35], v[178:181], v[194:197], v[32:35]
	v_mfma_f32_16x16x32_bf16 v[20:23], v[170:173], v[202:205], v[20:23]
	v_mfma_f32_16x16x32_bf16 v[16:19], v[178:181], v[202:205], v[16:19]
	v_mfma_f32_16x16x32_bf16 v[4:7], v[170:173], v[210:213], v[4:7]
	v_mfma_f32_16x16x32_bf16 v[0:3], v[178:181], v[210:213], v[0:3]
	s_barrier
	s_setprio 0
	s_andn2_b64 vcc, exec, s[44:45]
	s_mov_b64 s[46:47], -1
	s_mov_b64 s[44:45], 0
	s_mov_b64 s[48:49], 0x100
	s_cbranch_vccnz .Lkx_744
.LBB0_744:
	s_add_u32 s54, s42, s48
	s_addc_u32 s55, s43, s49
	s_add_u32 s52, s54, 0x100
	s_addc_u32 s53, s55, 0
	s_and_b64 s[50:51], s[46:47], exec
	s_cselect_b32 s51, s35, s53
	s_cselect_b32 s50, s82, s52
	s_add_u32 s48, s40, s48
	s_addc_u32 s49, s41, s49
	s_add_u32 s48, s48, 0x100
	s_addc_u32 s49, s49, 0
	s_and_b64 s[46:47], s[46:47], exec
	s_cselect_b32 s53, s31, s49
	s_cselect_b32 s52, s83, s48
	s_cselect_b32 s98, 1, 0
	s_add_u32 s56, s54, 0x10080
	ds_read_b128 v[150:153], v144
	ds_read_b128 v[154:157], v144 offset:1024
	ds_read_b128 v[158:161], v144 offset:2048
	ds_read_b128 v[162:165], v144 offset:3072
	ds_read_b128 v[166:169], v145
	ds_read_b128 v[170:173], v145 offset:1024
	ds_read_b128 v[174:177], v145 offset:2048
	ds_read_b128 v[178:181], v145 offset:3072
	s_addc_u32 s57, s55, 0
	s_add_i32 s93, s74, s60
	s_add_i32 m0, s61, 0xc000
	s_add_i32 s94, s61, 0xe000
	s_add_i32 s90, s93, 0x2000
	s_add_u32 s54, s52, 0x10000
	s_addc_u32 s55, s53, 0
	s_add_i32 s92, s75, s60
	s_add_i32 s91, s92, 0x2000
	s_add_i32 s89, 0, 0x18000
	s_add_i32 s88, 0, 0x1c000
	s_add_u32 s48, s50, 0x10000
	s_addc_u32 s49, s51, 0
	s_add_i32 s87, s89, s60
	s_add_i32 s85, s87, 0x2000
	s_add_u32 s46, s52, 0x10080
	s_addc_u32 s47, s53, 0
	s_add_i32 s86, s88, s60
	s_add_i32 s84, s86, 0x2000
	ds_read_b128 v[182:185], v146
	ds_read_b128 v[186:189], v146 offset:1024
	ds_read_b128 v[190:193], v146 offset:2048
	ds_read_b128 v[194:197], v146 offset:3072
	ds_read_b128 v[198:201], v146 offset:4096
	ds_read_b128 v[202:205], v146 offset:5120
	ds_read_b128 v[206:209], v146 offset:6144
	ds_read_b128 v[210:213], v146 offset:7168
	global_load_lds_dwordx4 v130, s[56:57]
	s_mov_b32 m0, s94
	s_nop 0
	global_load_lds_dwordx4 v128, s[56:57]
	s_waitcnt vmcnt(8)
	s_waitcnt lgkmcnt(0)
	s_setprio 1
	s_cmp_lg_u32 s98, 0
	s_cbranch_scc0 .Lkv_nopf
	v_lshl_add_u32 v138, s18, 8, v141
	v_ashrrev_i32_e32 v139, 31, v138
	v_lshl_add_u64 v[138:139], v[138:139], 4, s[14:15]
	global_load_dwordx4 v[222:225], v[138:139], off
	global_load_dwordx4 v[226:229], v[138:139], off offset:256
	global_load_dwordx4 v[230:233], v[138:139], off offset:512
	global_load_dwordx4 v[234:237], v[138:139], off offset:768
	global_load_dwordx4 v[238:241], v[138:139], off offset:2048
	global_load_dwordx4 v[242:245], v[138:139], off offset:2304
	global_load_dwordx4 v[248:251], v[138:139], off offset:2560
	global_load_dwordx4 v[252:255], v[138:139], off offset:2816
.Lkv_nopf:
	s_barrier
	v_mfma_f32_16x16x32_bf16 v[124:127], v[150:153], v[182:185], v[124:127]
	v_mfma_f32_16x16x32_bf16 v[120:123], v[158:161], v[182:185], v[120:123]
	v_mfma_f32_16x16x32_bf16 v[108:111], v[150:153], v[190:193], v[108:111]
	v_mfma_f32_16x16x32_bf16 v[104:107], v[158:161], v[190:193], v[104:107]
	v_mfma_f32_16x16x32_bf16 v[92:95], v[150:153], v[198:201], v[92:95]
	v_mfma_f32_16x16x32_bf16 v[88:91], v[158:161], v[198:201], v[88:91]
	v_mfma_f32_16x16x32_bf16 v[76:79], v[150:153], v[206:209], v[76:79]
	v_mfma_f32_16x16x32_bf16 v[72:75], v[158:161], v[206:209], v[72:75]
	v_mfma_f32_16x16x32_bf16 v[124:127], v[154:157], v[186:189], v[124:127]
	v_mfma_f32_16x16x32_bf16 v[120:123], v[162:165], v[186:189], v[120:123]
	v_mfma_f32_16x16x32_bf16 v[108:111], v[154:157], v[194:197], v[108:111]
	v_mfma_f32_16x16x32_bf16 v[104:107], v[162:165], v[194:197], v[104:107]
	v_mfma_f32_16x16x32_bf16 v[92:95], v[154:157], v[202:205], v[92:95]
	v_mfma_f32_16x16x32_bf16 v[88:91], v[162:165], v[202:205], v[88:91]
	v_mfma_f32_16x16x32_bf16 v[76:79], v[154:157], v[210:213], v[76:79]
	v_mfma_f32_16x16x32_bf16 v[72:75], v[162:165], v[210:213], v[72:75]
	v_mfma_f32_16x16x32_bf16 v[116:119], v[166:169], v[182:185], v[116:119]
	v_mfma_f32_16x16x32_bf16 v[112:115], v[174:177], v[182:185], v[112:115]
	v_mfma_f32_16x16x32_bf16 v[100:103], v[166:169], v[190:193], v[100:103]
	v_mfma_f32_16x16x32_bf16 v[96:99], v[174:177], v[190:193], v[96:99]
	v_mfma_f32_16x16x32_bf16 v[84:87], v[166:169], v[198:201], v[84:87]
	v_mfma_f32_16x16x32_bf16 v[80:83], v[174:177], v[198:201], v[80:83]
	v_mfma_f32_16x16x32_bf16 v[68:71], v[166:169], v[206:209], v[68:71]
	v_mfma_f32_16x16x32_bf16 v[64:67], v[174:177], v[206:209], v[64:67]
	v_mfma_f32_16x16x32_bf16 v[116:119], v[170:173], v[186:189], v[116:119]
	v_mfma_f32_16x16x32_bf16 v[112:115], v[178:181], v[186:189], v[112:115]
	v_mfma_f32_16x16x32_bf16 v[100:103], v[170:173], v[194:197], v[100:103]
	v_mfma_f32_16x16x32_bf16 v[96:99], v[178:181], v[194:197], v[96:99]
	v_mfma_f32_16x16x32_bf16 v[84:87], v[170:173], v[202:205], v[84:87]
	v_mfma_f32_16x16x32_bf16 v[80:83], v[178:181], v[202:205], v[80:83]
	v_mfma_f32_16x16x32_bf16 v[68:71], v[170:173], v[210:213], v[68:71]
	v_mfma_f32_16x16x32_bf16 v[64:67], v[178:181], v[210:213], v[64:67]
	s_barrier
	s_setprio 0
	s_mov_b32 m0, s93
	s_add_u32 s98, s52, 0x80
	s_addc_u32 s99, s53, 0
	ds_read_b128 v[182:185], v146 offset:16384
	ds_read_b128 v[186:189], v146 offset:17408
	ds_read_b128 v[190:193], v146 offset:18432
	ds_read_b128 v[194:197], v146 offset:19456
	ds_read_b128 v[198:201], v146 offset:20480
	ds_read_b128 v[202:205], v146 offset:21504
	ds_read_b128 v[206:209], v146 offset:22528
	ds_read_b128 v[210:213], v146 offset:23552
	global_load_lds_dwordx4 v130, s[52:53]
	s_mov_b32 m0, s90
	s_nop 0
	global_load_lds_dwordx4 v128, s[52:53]
	s_mov_b32 m0, s92
	s_add_u32 s100, s50, 0x80
	s_addc_u32 s101, s51, 0
	global_load_lds_dwordx4 v130, s[54:55]
	s_mov_b32 m0, s91
	s_nop 0
	global_load_lds_dwordx4 v128, s[54:55]
	s_mov_b32 m0, s61
	s_nop 0
	global_load_lds_dwordx4 v130, s[50:51]
	s_mov_b32 m0, s62
	s_nop 0
	global_load_lds_dwordx4 v128, s[50:51]
	s_waitcnt vmcnt(8)
	s_waitcnt lgkmcnt(0)
	s_setprio 1
	s_barrier
	v_mfma_f32_16x16x32_bf16 v[60:63], v[150:153], v[182:185], v[60:63]
	v_mfma_f32_16x16x32_bf16 v[56:59], v[158:161], v[182:185], v[56:59]
	v_mfma_f32_16x16x32_bf16 v[44:47], v[150:153], v[190:193], v[44:47]
	v_mfma_f32_16x16x32_bf16 v[40:43], v[158:161], v[190:193], v[40:43]
	v_mfma_f32_16x16x32_bf16 v[28:31], v[150:153], v[198:201], v[28:31]
	v_mfma_f32_16x16x32_bf16 v[24:27], v[158:161], v[198:201], v[24:27]
	v_mfma_f32_16x16x32_bf16 v[12:15], v[150:153], v[206:209], v[12:15]
	v_mfma_f32_16x16x32_bf16 v[8:11], v[158:161], v[206:209], v[8:11]
	v_mfma_f32_16x16x32_bf16 v[60:63], v[154:157], v[186:189], v[60:63]
	v_mfma_f32_16x16x32_bf16 v[56:59], v[162:165], v[186:189], v[56:59]
	v_mfma_f32_16x16x32_bf16 v[44:47], v[154:157], v[194:197], v[44:47]
	v_mfma_f32_16x16x32_bf16 v[40:43], v[162:165], v[194:197], v[40:43]
	v_mfma_f32_16x16x32_bf16 v[28:31], v[154:157], v[202:205], v[28:31]
	v_mfma_f32_16x16x32_bf16 v[24:27], v[162:165], v[202:205], v[24:27]
	v_mfma_f32_16x16x32_bf16 v[12:15], v[154:157], v[210:213], v[12:15]
	v_mfma_f32_16x16x32_bf16 v[8:11], v[162:165], v[210:213], v[8:11]
	v_mfma_f32_16x16x32_bf16 v[52:55], v[166:169], v[182:185], v[52:55]
	v_mfma_f32_16x16x32_bf16 v[48:51], v[174:177], v[182:185], v[48:51]
	v_mfma_f32_16x16x32_bf16 v[36:39], v[166:169], v[190:193], v[36:39]
	v_mfma_f32_16x16x32_bf16 v[32:35], v[174:177], v[190:193], v[32:35]
	v_mfma_f32_16x16x32_bf16 v[20:23], v[166:169], v[198:201], v[20:23]
	v_mfma_f32_16x16x32_bf16 v[16:19], v[174:177], v[198:201], v[16:19]
	v_mfma_f32_16x16x32_bf16 v[4:7], v[166:169], v[206:209], v[4:7]
	v_mfma_f32_16x16x32_bf16 v[0:3], v[174:177], v[206:209], v[0:3]
	v_mfma_f32_16x16x32_bf16 v[52:55], v[170:173], v[186:189], v[52:55]
	v_mfma_f32_16x16x32_bf16 v[48:51], v[178:181], v[186:189], v[48:51]
	v_mfma_f32_16x16x32_bf16 v[36:39], v[170:173], v[194:197], v[36:39]
	v_mfma_f32_16x16x32_bf16 v[32:35], v[178:181], v[194:197], v[32:35]
	v_mfma_f32_16x16x32_bf16 v[20:23], v[170:173], v[202:205], v[20:23]
	v_mfma_f32_16x16x32_bf16 v[16:19], v[178:181], v[202:205], v[16:19]
	v_mfma_f32_16x16x32_bf16 v[4:7], v[170:173], v[210:213], v[4:7]
	v_mfma_f32_16x16x32_bf16 v[0:3], v[178:181], v[210:213], v[0:3]
	s_barrier
	s_setprio 0
	v_add_u32_e32 v132, s89, v143
	ds_read_b128 v[150:153], v132
	ds_read_b128 v[154:157], v132 offset:1024
	ds_read_b128 v[158:161], v132 offset:2048
	ds_read_b128 v[162:165], v132 offset:3072
	v_add_u32_e32 v132, s88, v143
	ds_read_b128 v[166:169], v132
	ds_read_b128 v[170:173], v132 offset:1024
	ds_read_b128 v[174:177], v132 offset:2048
	ds_read_b128 v[178:181], v132 offset:3072
	s_mov_b32 m0, s63
	ds_read_b128 v[182:185], v146 offset:32768
	ds_read_b128 v[186:189], v146 offset:33792
	ds_read_b128 v[190:193], v146 offset:34816
	ds_read_b128 v[194:197], v146 offset:35840
	ds_read_b128 v[198:201], v146 offset:36864
	ds_read_b128 v[202:205], v146 offset:37888
	ds_read_b128 v[206:209], v146 offset:38912
	ds_read_b128 v[210:213], v146 offset:39936
	global_load_lds_dwordx4 v130, s[48:49]
	s_mov_b32 m0, s64
	s_nop 0
	global_load_lds_dwordx4 v128, s[48:49]
	s_waitcnt vmcnt(8)
	s_waitcnt lgkmcnt(0)
	s_setprio 1
	s_barrier
	v_mfma_f32_16x16x32_bf16 v[124:127], v[150:153], v[182:185], v[124:127]
	v_mfma_f32_16x16x32_bf16 v[120:123], v[158:161], v[182:185], v[120:123]
	v_mfma_f32_16x16x32_bf16 v[108:111], v[150:153], v[190:193], v[108:111]
	v_mfma_f32_16x16x32_bf16 v[104:107], v[158:161], v[190:193], v[104:107]
	v_mfma_f32_16x16x32_bf16 v[92:95], v[150:153], v[198:201], v[92:95]
	v_mfma_f32_16x16x32_bf16 v[88:91], v[158:161], v[198:201], v[88:91]
	v_mfma_f32_16x16x32_bf16 v[76:79], v[150:153], v[206:209], v[76:79]
	v_mfma_f32_16x16x32_bf16 v[72:75], v[158:161], v[206:209], v[72:75]
	v_mfma_f32_16x16x32_bf16 v[124:127], v[154:157], v[186:189], v[124:127]
	v_mfma_f32_16x16x32_bf16 v[120:123], v[162:165], v[186:189], v[120:123]
	v_mfma_f32_16x16x32_bf16 v[108:111], v[154:157], v[194:197], v[108:111]
	v_mfma_f32_16x16x32_bf16 v[104:107], v[162:165], v[194:197], v[104:107]
	v_mfma_f32_16x16x32_bf16 v[92:95], v[154:157], v[202:205], v[92:95]
	v_mfma_f32_16x16x32_bf16 v[88:91], v[162:165], v[202:205], v[88:91]
	v_mfma_f32_16x16x32_bf16 v[76:79], v[154:157], v[210:213], v[76:79]
	v_mfma_f32_16x16x32_bf16 v[72:75], v[162:165], v[210:213], v[72:75]
	v_mfma_f32_16x16x32_bf16 v[116:119], v[166:169], v[182:185], v[116:119]
	v_mfma_f32_16x16x32_bf16 v[112:115], v[174:177], v[182:185], v[112:115]
	v_mfma_f32_16x16x32_bf16 v[100:103], v[166:169], v[190:193], v[100:103]
	v_mfma_f32_16x16x32_bf16 v[96:99], v[174:177], v[190:193], v[96:99]
	v_mfma_f32_16x16x32_bf16 v[84:87], v[166:169], v[198:201], v[84:87]
	v_mfma_f32_16x16x32_bf16 v[80:83], v[174:177], v[198:201], v[80:83]
	v_mfma_f32_16x16x32_bf16 v[68:71], v[166:169], v[206:209], v[68:71]
	v_mfma_f32_16x16x32_bf16 v[64:67], v[174:177], v[206:209], v[64:67]
	v_mfma_f32_16x16x32_bf16 v[116:119], v[170:173], v[186:189], v[116:119]
	v_mfma_f32_16x16x32_bf16 v[112:115], v[178:181], v[186:189], v[112:115]
	v_mfma_f32_16x16x32_bf16 v[100:103], v[170:173], v[194:197], v[100:103]
	v_mfma_f32_16x16x32_bf16 v[96:99], v[178:181], v[194:197], v[96:99]
	v_mfma_f32_16x16x32_bf16 v[84:87], v[170:173], v[202:205], v[84:87]
	v_mfma_f32_16x16x32_bf16 v[80:83], v[178:181], v[202:205], v[80:83]
	v_mfma_f32_16x16x32_bf16 v[68:71], v[170:173], v[210:213], v[68:71]
	v_mfma_f32_16x16x32_bf16 v[64:67], v[178:181], v[210:213], v[64:67]
	s_barrier
	s_setprio 0
	s_mov_b32 m0, s87
	ds_read_b128 v[182:185], v146 offset:49152
	ds_read_b128 v[186:189], v146 offset:50176
	ds_read_b128 v[190:193], v146 offset:51200
	ds_read_b128 v[194:197], v146 offset:52224
	ds_read_b128 v[198:201], v146 offset:53248
	ds_read_b128 v[202:205], v146 offset:54272
	ds_read_b128 v[206:209], v146 offset:55296
	ds_read_b128 v[210:213], v146 offset:56320
	global_load_lds_dwordx4 v130, s[98:99]
	s_mov_b32 m0, s85
	s_nop 0
	global_load_lds_dwordx4 v128, s[98:99]
	s_mov_b32 m0, s86
	s_nop 0
	global_load_lds_dwordx4 v130, s[46:47]
	s_mov_b32 m0, s84
	s_nop 0
	global_load_lds_dwordx4 v128, s[46:47]
	s_mov_b32 m0, s70
	s_nop 0
	global_load_lds_dwordx4 v130, s[100:101]
	s_mov_b32 m0, s71
	s_nop 0
	global_load_lds_dwordx4 v128, s[100:101]
	s_waitcnt vmcnt(8)
	s_waitcnt lgkmcnt(0)
	s_setprio 1
	s_barrier
	v_mfma_f32_16x16x32_bf16 v[60:63], v[150:153], v[182:185], v[60:63]
	v_mfma_f32_16x16x32_bf16 v[56:59], v[158:161], v[182:185], v[56:59]
	v_mfma_f32_16x16x32_bf16 v[44:47], v[150:153], v[190:193], v[44:47]
	v_mfma_f32_16x16x32_bf16 v[40:43], v[158:161], v[190:193], v[40:43]
	v_mfma_f32_16x16x32_bf16 v[28:31], v[150:153], v[198:201], v[28:31]
	v_mfma_f32_16x16x32_bf16 v[24:27], v[158:161], v[198:201], v[24:27]
	v_mfma_f32_16x16x32_bf16 v[12:15], v[150:153], v[206:209], v[12:15]
	v_mfma_f32_16x16x32_bf16 v[8:11], v[158:161], v[206:209], v[8:11]
	v_mfma_f32_16x16x32_bf16 v[60:63], v[154:157], v[186:189], v[60:63]
	v_mfma_f32_16x16x32_bf16 v[56:59], v[162:165], v[186:189], v[56:59]
	v_mfma_f32_16x16x32_bf16 v[44:47], v[154:157], v[194:197], v[44:47]
	v_mfma_f32_16x16x32_bf16 v[40:43], v[162:165], v[194:197], v[40:43]
	v_mfma_f32_16x16x32_bf16 v[28:31], v[154:157], v[202:205], v[28:31]
	v_mfma_f32_16x16x32_bf16 v[24:27], v[162:165], v[202:205], v[24:27]
	v_mfma_f32_16x16x32_bf16 v[12:15], v[154:157], v[210:213], v[12:15]
	v_mfma_f32_16x16x32_bf16 v[8:11], v[162:165], v[210:213], v[8:11]
	v_mfma_f32_16x16x32_bf16 v[52:55], v[166:169], v[182:185], v[52:55]
	v_mfma_f32_16x16x32_bf16 v[48:51], v[174:177], v[182:185], v[48:51]
	v_mfma_f32_16x16x32_bf16 v[36:39], v[166:169], v[190:193], v[36:39]
	v_mfma_f32_16x16x32_bf16 v[32:35], v[174:177], v[190:193], v[32:35]
	v_mfma_f32_16x16x32_bf16 v[20:23], v[166:169], v[198:201], v[20:23]
	v_mfma_f32_16x16x32_bf16 v[16:19], v[174:177], v[198:201], v[16:19]
	v_mfma_f32_16x16x32_bf16 v[4:7], v[166:169], v[206:209], v[4:7]
	v_mfma_f32_16x16x32_bf16 v[0:3], v[174:177], v[206:209], v[0:3]
	v_mfma_f32_16x16x32_bf16 v[52:55], v[170:173], v[186:189], v[52:55]
	v_mfma_f32_16x16x32_bf16 v[48:51], v[178:181], v[186:189], v[48:51]
	v_mfma_f32_16x16x32_bf16 v[36:39], v[170:173], v[194:197], v[36:39]
	v_mfma_f32_16x16x32_bf16 v[32:35], v[178:181], v[194:197], v[32:35]
	v_mfma_f32_16x16x32_bf16 v[20:23], v[170:173], v[202:205], v[20:23]
	v_mfma_f32_16x16x32_bf16 v[16:19], v[178:181], v[202:205], v[16:19]
	v_mfma_f32_16x16x32_bf16 v[4:7], v[170:173], v[210:213], v[4:7]
	v_mfma_f32_16x16x32_bf16 v[0:3], v[178:181], v[210:213], v[0:3]
	s_barrier
	s_setprio 0
	s_andn2_b64 vcc, exec, s[44:45]
	s_mov_b64 s[46:47], -1
	s_mov_b64 s[44:45], 0
	s_mov_b64 s[48:49], 0x100
	s_cbranch_vccz .LBB0_744
